# grid barrier: non-leader workgroups poll the cross-XCC generation word directly instead of the per-XCC relay
# speedup vs baseline: 1.1611x; 1.0073x over previous
.LBB0_1466:
	s_or_b64 exec, exec, s[4:5]
	v_cvt_f32_u32_e32 v4, v2
	s_waitcnt vmcnt(0)
	v_readfirstlane_b32 s4, v3
	v_sub_u32_e32 v3, 0, v2
	v_rcp_iflag_f32_e32 v4, v4
	v_add_u32_e32 v5, s4, v1
	v_mul_f32_e32 v4, 0x4f7ffffe, v4
	v_cvt_u32_f32_e32 v4, v4
	v_mul_lo_u32 v1, v3, v4
	v_mul_hi_u32 v1, v4, v1
	v_add_u32_e32 v1, v4, v1
	v_mul_hi_u32 v1, v5, v1
	v_mul_lo_u32 v3, v1, v2
	v_sub_u32_e32 v3, v5, v3
	v_add_u32_e32 v4, 1, v1
	v_cmp_ge_u32_e32 vcc, v3, v2
	s_nop 1
	v_cndmask_b32_e32 v1, v1, v4, vcc
	v_sub_u32_e32 v4, v3, v2
	v_cndmask_b32_e32 v3, v3, v4, vcc
	v_add_u32_e32 v4, 1, v1
	v_cmp_ge_u32_e32 vcc, v3, v2
	v_add_u32_e32 v3, 1, v5
	s_nop 0
	v_cndmask_b32_e32 v1, v1, v4, vcc
	v_mul_lo_u32 v4, v2, v1
	v_add_u32_e32 v2, v4, v2
	v_cmp_ne_u32_e32 vcc, v3, v2
	s_and_saveexec_b64 s[4:5], vcc
	s_xor_b64 s[4:5], exec, s[4:5]
	s_cbranch_execz .LBB0_1493
	v_readlane_b32 s8, v240, 30
	v_readlane_b32 s9, v240, 31
	s_nop 4
	global_load_dword v0, v125, s[8:9] sc1
	s_waitcnt vmcnt(0)
	v_cmp_eq_u32_e32 vcc, v0, v1
	s_and_saveexec_b64 s[8:9], vcc
	s_cbranch_execz .LBB0_1479
	s_mov_b32 s26, s18
	s_mov_b64 s[24:25], s[16:17]
	s_mov_b32 s21, 1
	s_mov_b64 s[10:11], 0
	s_branch .LBB0_1470

.LBB0_1472:
	v_readlane_b32 s14, v240, 30
	v_readlane_b32 s15, v240, 31
	s_add_i32 s21, s21, 1
	s_mov_b64 s[16:17], -1
	s_nop 2
	global_load_dword v0, v125, s[14:15] sc1
	s_waitcnt vmcnt(0)
	v_cmp_ne_u32_e32 vcc, v0, v1
	s_orn2_b64 s[14:15], vcc, exec
	s_branch .LBB0_1469
